# same as previous minus the static s_setprio (no effect): GEMM1 tile-schedule rotation, deferred generic epilogue stores, seg1 table-load hoist, NSA K-fragment read hoist
# baseline (speedup 1.0000x reference)
; DI void phase_attn(const Params& p, char* smem, int ulo, int uhi, int cidx) {
;   unsigned* ctr = (unsigned*)(p.ws + WS_CTR) + cidx;
;   int* su = (int*)(smem + LDS_IMG + 16);
;   unsigned* pend = nullptr;
;   int nextu = 0;
;   if (threadIdx.x == 0) nextu = ulo + (int)blockIdx.x;
;   for (;;) {
.LBB0_340:
	s_or_b64 exec, exec, s[0:1]
	s_add_u32 s52, s70, 0x1bd34000
	s_addc_u32 s53, s71, 0
	s_cmp_gt_i32 s78, 1
	s_cselect_b64 s[54:55], -1, 0
	s_add_u32 s0, s70, 0x1950c000
	v_writelane_b32 v255, s0, 16
	s_addc_u32 s0, s71, 0
	v_writelane_b32 v255, s0, 17
	s_add_u32 s0, s70, 0x1bd34040
	v_writelane_b32 v255, s0, 18
	s_addc_u32 s0, s71, 0
	v_writelane_b32 v255, s0, 19
	s_add_u32 s0, s70, 0x1930c000
	v_writelane_b32 v255, s0, 20
	s_addc_u32 s0, s71, 0
	v_writelane_b32 v255, s0, 21
	s_add_u32 s0, s70, 0x1a12c000
	s_addc_u32 s1, s71, 0
	v_writelane_b32 v255, s0, 22
	v_mov_b32_e32 v207, 0
	v_mov_b32_e32 v254, 0x24010
	v_writelane_b32 v255, s1, 23
	s_add_u32 s0, s70, 0x1bd34140
	v_writelane_b32 v255, s0, 24
	s_addc_u32 s0, s71, 0
	v_writelane_b32 v255, s0, 25
	s_add_u32 s0, s70, 0x1b934000
	v_writelane_b32 v255, s0, 26
	s_addc_u32 s0, s71, 0
	v_writelane_b32 v255, s0, 27
	s_add_u32 s0, s70, 0x1bd34100
	v_writelane_b32 v255, s0, 28
	s_addc_u32 s0, s71, 0
	v_writelane_b32 v255, s0, 29
	s_add_u32 s0, s68, 0x4000000
	v_writelane_b32 v255, s0, 30
	s_addc_u32 s0, s69, 0
	v_writelane_b32 v255, s0, 31
	s_add_u32 s0, s70, 0x1b534000
	v_writelane_b32 v255, s0, 32
	s_addc_u32 s0, s71, 0
	v_writelane_b32 v255, s0, 33
	s_add_u32 s0, s70, 0x1990c000
	v_writelane_b32 v255, s0, 34
	s_addc_u32 s0, s71, 0
	v_writelane_b32 v255, s0, 35
	s_add_u32 s0, s70, 0x1930c200
	v_writelane_b32 v255, s0, 36
	s_addc_u32 s0, s71, 0
	v_writelane_b32 v255, s0, 37
	s_add_u32 s0, s70, 0x301c80
	s_addc_u32 s1, s71, 0
	v_writelane_b32 v255, s0, 38
	s_movk_i32 s60, 0xc0
	s_mov_b64 s[82:83], 0x20000
	v_writelane_b32 v255, s1, 39
	s_mov_b64 s[0:1], 0
	s_mov_b64 s[84:85], 0x40000
	s_mov_b64 s[86:87], 0x60000
	s_movk_i32 s76, 0x4000
	s_mov_b64 s[88:89], 0x80
	s_mov_b64 s[90:91], 0x20080
	s_mov_b64 s[94:95], 0x60080
	s_movk_i32 s61, 0x80
	s_movk_i32 s75, 0x90
	s_movk_i32 s77, 0xa0
	s_movk_i32 s79, 0xb0
	s_movk_i32 s92, 0x1000
	s_movk_i32 s93, 0x3000
	s_mov_b32 s57, 0x40000
	s_movk_i32 s72, 0x70
	s_movk_i32 s46, 0x50
	s_movk_i32 s47, 0x60
	s_mov_b32 s73, 0x41000000
	v_mov_b32_e32 v228, 0x358637bd
	v_mov_b32_e32 v229, 0x3000
	v_mov_b32_e32 v230, 0x42800000
	v_mov_b32_e32 v231, 0x42000000
	v_mov_b32_e32 v232, 0xf149f2ca
	v_mbcnt_hi_u32_b32 v222, -1, v1
	v_mov_b32_e32 v233, 0x7149f2ca
	s_mov_b32 s74, 0xefa18f08
	s_mov_b64 s[96:97], 0x80000
	s_mov_b64 s[34:35], 0x2000
	s_mov_b32 s56, 0x3e0293ee
	s_mov_b32 s41, 0
	s_waitcnt lgkmcnt(0)
	s_barrier
	s_branch .LBB0_344
